# sub-barrier spin and sample-tail helper poll back off with s_sleep 1 (was 2 / 4)
# baseline (speedup 1.0000x reference)
.LBB0_219:
	global_load_dword v1, v0, s[4:5] sc1
	s_mov_b64 s[6:7], -1
	s_waitcnt vmcnt(0)
	v_cmp_lt_u32_e32 vcc, 15, v1
	s_cbranch_vccnz .LBB0_218
	s_sleep 1
	global_load_dword v1, v0, s[4:5] sc1
	s_waitcnt vmcnt(0)
	v_cmp_gt_u32_e32 vcc, 16, v1
	s_cbranch_vccz .LBB0_218
	s_sleep 1
	global_load_dword v1, v0, s[4:5] sc1
	s_waitcnt vmcnt(0)
	v_cmp_gt_u32_e32 vcc, 16, v1
	s_cbranch_vccz .LBB0_218
	s_sleep 1
	global_load_dword v1, v0, s[4:5] sc1
	s_waitcnt vmcnt(0)
	v_cmp_gt_u32_e32 vcc, 16, v1
	s_cbranch_vccz .LBB0_218
	s_sleep 1
	global_load_dword v1, v0, s[4:5] sc1
	s_waitcnt vmcnt(0)
	v_cmp_gt_u32_e32 vcc, 16, v1
	s_cbranch_vccz .LBB0_218
	s_add_i32 s8, s8, -5
	s_cmp_eq_u32 s8, 0
	s_cselect_b64 s[6:7], -1, 0
	s_sleep 1
	s_branch .LBB0_218

ATH0_POLL:
	global_load_dword v237, v236, s[78:79] sc1
	s_waitcnt vmcnt(0)
	v_readfirstlane_b32 s0, v237
	s_cmp_ge_u32 s0, 16
	s_cbranch_scc1 ATH0_GO
	s_sleep 1
	s_add_i32 s1, s1, -1
	s_cmp_eq_u32 s1, 0
	s_cbranch_scc0 ATH0_POLL
	s_branch .LBB0_307

ATH1_POLL:
	global_load_dword v237, v236, s[78:79] sc1
	s_waitcnt vmcnt(0)
	v_readfirstlane_b32 s0, v237
	s_cmp_ge_u32 s0, 16
	s_cbranch_scc1 ATH1_GO
	s_sleep 1
	s_add_i32 s1, s1, -1
	s_cmp_eq_u32 s1, 0
	s_cbranch_scc0 ATH1_POLL
	s_branch .LBB0_1015

ATH2_POLL:
	global_load_dword v237, v236, s[78:79] sc1
	s_waitcnt vmcnt(0)
	v_readfirstlane_b32 s0, v237
	s_cmp_ge_u32 s0, 16
	s_cbranch_scc1 ATH2_GO
	s_sleep 1
	s_add_i32 s1, s1, -1
	s_cmp_eq_u32 s1, 0
	s_cbranch_scc0 ATH2_POLL
	s_branch .LBB0_1724

ATH3_POLL:
	global_load_dword v237, v236, s[78:79] sc1
	s_waitcnt vmcnt(0)
	v_readfirstlane_b32 s0, v237
	s_cmp_ge_u32 s0, 16
	s_cbranch_scc1 ATH3_GO
	s_sleep 1
	s_add_i32 s1, s1, -1
	s_cmp_eq_u32 s1, 0
	s_cbranch_scc0 ATH3_POLL
	s_branch .LBB0_2433
